# spatial unit top wait relaxed: the attention epilogue's output stores stay in flight under the unit's address set-up
# speedup vs baseline: 1.0019x; 1.0019x over previous
.LBB0_964:
	s_cmpk_gt_i32 s92, 0xff
	s_cbranch_scc1 .LBB0_973
	s_add_u32 s76, s74, 0x4b00000
	s_addc_u32 s77, s75, 0
	v_readlane_b32 s26, v253, 19
	v_readlane_b32 s27, v253, 20
	v_lshrrev_b32_e32 v3, 6, v215
	v_lshrrev_b32_e32 v7, 5, v214
	v_and_b32_e32 v8, 31, v214
	v_lshlrev_b32_e32 v8, 4, v8
	v_lshl_add_u32 v9, v3, 4, v7
	v_lshl_add_u32 v4, v9, 9, v8
	s_and_b32 s10, s92, 3
	s_lshl_b32 s11, s10, 16
	v_add_u32_e32 v4, s11, v4
	v_add_u32_e32 v5, 0x1000, v4
	global_load_dwordx4 v[216:219], v4, s[26:27]
	global_load_dwordx4 v[220:223], v4, s[26:27] offset:1024
	global_load_dwordx4 v[224:227], v4, s[26:27] offset:2048
	global_load_dwordx4 v[228:231], v4, s[26:27] offset:3072
	global_load_dwordx4 v[232:235], v5, s[26:27]
	global_load_dwordx4 v[236:239], v5, s[26:27] offset:1024
	global_load_dwordx4 v[240:243], v5, s[26:27] offset:2048
	global_load_dwordx4 v[244:247], v5, s[26:27] offset:3072
	v_lshrrev_b32_e32 v7, 4, v214
	v_and_b32_e32 v8, 15, v214
	v_lshlrev_b32_e32 v8, 4, v8
	v_lshl_add_u32 v9, v3, 4, v7
	s_lshl_b32 s11, s10, 7
	v_add_u32_e32 v9, s11, v9
	v_lshlrev_b32_e32 v9, 14, v9
	s_lshr_b32 s11, s92, 2
	s_lshl_b32 s11, s11, 8
	v_add3_u32 v9, v9, v8, s11
	v_add_u32_e32 v11, 0x10000, v9
	global_load_dwordx4 v[178:181], v9, s[76:77]
	global_load_dwordx4 v[182:185], v11, s[76:77]
	v_add_u32_e32 v9, 0x20000, v9
	v_add_u32_e32 v11, 0x20000, v11
	global_load_dwordx4 v[186:189], v9, s[76:77]
	global_load_dwordx4 v[190:193], v11, s[76:77]
	s_waitcnt vmcnt(21)
	v_mov_b32_e32 v133, 0
	s_add_u32 s2, s74, 0x5300000
	v_mov_b32_e32 v149, v133
	s_addc_u32 s3, s75, 0
	v_readlane_b32 s12, v253, 5
	v_lshl_add_u64 v[0:1], s[74:75], 0, v[148:149]
	s_mov_b64 s[10:11], 0x4b00000
	s_add_u32 s6, s74, 0x1d00000
	s_movk_i32 s4, 0x80
	v_lshlrev_b32_e32 v2, 7, v198
	v_lshlrev_b32_e32 v132, 2, v157
	v_readlane_b32 s16, v253, 9
	v_readlane_b32 s17, v253, 10
	v_readlane_b32 s20, v253, 13
	v_readlane_b32 s26, v253, 19
	v_readlane_b32 s27, v253, 20
	v_lshlrev_b32_e32 v136, 6, v146
	v_lshl_add_u64 v[138:139], v[0:1], 0, s[10:11]
	v_mbcnt_lo_u32_b32 v0, -1, 0
	s_addc_u32 s7, s75, 0
	v_cmp_gt_u32_e64 s[4:5], s4, v215
	v_lshl_add_u64 v[134:135], s[26:27], 0, v[132:133]
	s_mov_b32 s11, 0
	v_lshl_add_u32 v137, v215, 2, 0
	v_lshl_add_u32 v164, v147, 5, 0
	s_lshl_b32 s16, s92, 5
	s_lshl_b32 s17, s96, 5
	s_movk_i32 s20, 0x90
	v_lshlrev_b32_e32 v165, 2, v2
	v_lshlrev_b32_e32 v140, 1, v136
	v_mov_b32_e32 v141, v133
	v_lshlrev_b32_e32 v142, 1, v197
	v_mov_b32_e32 v143, v133
	v_mov_b32_e32 v166, 0x358637bd
	v_lshlrev_b32_e32 v144, 2, v146
	v_mbcnt_hi_u32_b32 v167, -1, v0
	v_readlane_b32 s13, v253, 6
	v_readlane_b32 s14, v253, 7
	v_readlane_b32 s15, v253, 8
	v_readlane_b32 s18, v253, 11
	v_readlane_b32 s19, v253, 12
	v_readlane_b32 s21, v253, 14
	v_readlane_b32 s22, v253, 15
	v_readlane_b32 s23, v253, 16
	v_readlane_b32 s24, v253, 17
	v_readlane_b32 s25, v253, 18
	s_branch .LBB0_967
